# phase-head hoist: grid-barrier wait (TOP poll + inv + WG barrier) moved after the common scalar phase head so the head overlaps the barrier round
# baseline (speedup 1.0000x reference)
.LBB0_14:
	s_and_b32 s81, s9, 0xffffffc0
	s_cmpk_gt_i32 s93, 0xff
	s_cselect_b64 s[82:83], -1, 0
	s_add_u32 s84, s0, 0x4200
	s_addc_u32 s85, s1, 0
	s_add_u32 s86, s0, 0x4400
	s_addc_u32 s87, s1, 0
	s_add_u32 s60, s0, 0x4500
	s_addc_u32 s61, s1, 0
	s_add_u32 s76, s0, 0x4600
	s_addc_u32 s77, s1, 0
	s_add_u32 s78, s0, 0x4700
	s_addc_u32 s79, s1, 0
	s_add_u32 s64, s0, 0x4800
	s_addc_u32 s65, s1, 0
	s_add_u32 s66, s0, 0x4900
	s_addc_u32 s67, s1, 0
	s_add_u32 s68, s0, 0x4a00
	s_addc_u32 s69, s1, 0
	s_add_u32 s62, s0, 0x4b00
	s_addc_u32 s63, s1, 0
	s_add_u32 s72, s0, 0x4c00
	s_addc_u32 s73, s1, 0
	s_add_u32 s4, s0, 0x4d00
	s_addc_u32 s5, s1, 0
	v_writelane_b32 v250, s4, 2
	v_mbcnt_lo_u32_b32 v0, -1, 0
	v_mov_b32_e32 v209, 0
	v_writelane_b32 v250, s5, 3
	s_add_u32 s4, s0, 0x4e00
	s_addc_u32 s5, s1, 0
	v_writelane_b32 v250, s4, 4
	v_mov_b32_e32 v222, 0x358637bd
	v_mbcnt_hi_u32_b32 v226, -1, v0
	v_writelane_b32 v250, s5, 5
	s_add_u32 s4, s0, 0x4f00
	s_addc_u32 s5, s1, 0
	v_writelane_b32 v250, s4, 6
	v_mov_b64_e32 v[212:213], 0xff
	v_mov_b32_e32 v227, 0x41b17218
	v_writelane_b32 v250, s5, 7
	s_add_u32 s4, s0, 0x5000
	s_addc_u32 s5, s1, 0
	v_writelane_b32 v250, s4, 8
	v_mov_b32_e32 v228, 0xff800000
	v_not_b32_e32 v231, 27
	v_writelane_b32 v250, s5, 9
	s_add_u32 s4, s0, 0x5100
	s_addc_u32 s5, s1, 0
	v_writelane_b32 v250, s4, 10
	s_movk_i32 s59, 0x3ff
	s_movk_i32 s71, 0xc0
	v_writelane_b32 v250, s5, 11
	s_add_u32 s4, s0, 0x5200
	s_addc_u32 s5, s1, 0
	v_writelane_b32 v250, s4, 12
	s_movk_i32 s70, 0x2000
	s_mov_b32 s58, 0x10000
	v_writelane_b32 v250, s5, 13
	s_add_u32 s4, s0, 0x5300
	s_addc_u32 s5, s1, 0
	v_writelane_b32 v250, s4, 14
	s_cmp_eq_u32 s8, 15
	s_mov_b32 s51, 0x12000
	v_writelane_b32 v250, s5, 15
	s_cselect_b64 s[4:5], -1, 0
	v_writelane_b32 v250, s4, 16
	s_cmp_eq_u32 s8, 14
	s_mov_b32 s56, 0x16000
	v_writelane_b32 v250, s5, 17
	s_cselect_b64 s[4:5], -1, 0
	v_writelane_b32 v250, s4, 18
	s_cmp_eq_u32 s8, 13
	s_movk_i32 s50, 0x4000
	v_writelane_b32 v250, s5, 19
	s_cselect_b64 s[4:5], -1, 0
	v_writelane_b32 v250, s4, 20
	s_cmp_eq_u32 s8, 12
	s_movk_i32 s33, 0x6000
	v_writelane_b32 v250, s5, 21
	s_cselect_b64 s[4:5], -1, 0
	v_writelane_b32 v250, s4, 22
	s_cmp_eq_u32 s8, 11
	s_movk_i32 s89, 0x1800
	v_writelane_b32 v250, s5, 23
	s_cselect_b64 s[4:5], -1, 0
	v_writelane_b32 v250, s4, 24
	s_cmp_eq_u32 s8, 10
	s_mov_b32 s55, 0
	v_writelane_b32 v250, s5, 25
	s_cselect_b64 s[4:5], -1, 0
	v_writelane_b32 v250, s4, 26
	s_cmp_eq_u32 s8, 9
	s_mov_b64 s[24:25], 0x80
	v_writelane_b32 v250, s5, 27
	s_cselect_b64 s[4:5], -1, 0
	v_writelane_b32 v250, s4, 28
	s_cmp_eq_u32 s8, 8
	s_nop 0
	v_writelane_b32 v250, s5, 29
	s_cselect_b64 s[4:5], -1, 0
	v_writelane_b32 v250, s4, 30
	s_cmp_eq_u32 s8, 7
	s_nop 0
	v_writelane_b32 v250, s5, 31
	s_cselect_b64 s[4:5], -1, 0
	v_writelane_b32 v250, s4, 32
	s_cmp_eq_u32 s8, 6
	s_nop 0
	v_writelane_b32 v250, s5, 33
	s_cselect_b64 s[4:5], -1, 0
	v_writelane_b32 v250, s4, 34
	s_cmp_eq_u32 s8, 5
	s_nop 0
	v_writelane_b32 v250, s5, 35
	s_cselect_b64 s[4:5], -1, 0
	v_writelane_b32 v250, s4, 36
	s_cmp_eq_u32 s8, 4
	s_nop 0
	v_writelane_b32 v250, s5, 37
	s_cselect_b64 s[4:5], -1, 0
	v_writelane_b32 v250, s4, 38
	s_cmp_eq_u32 s8, 3
	s_nop 0
	v_writelane_b32 v250, s5, 39
	s_cselect_b64 s[4:5], -1, 0
	v_writelane_b32 v250, s4, 40
	s_cmp_eq_u32 s8, 2
	s_nop 0
	v_writelane_b32 v250, s5, 41
	s_cselect_b64 s[4:5], -1, 0
	v_writelane_b32 v250, s4, 42
	s_cmp_eq_u32 s8, 1
	s_nop 0
	v_writelane_b32 v250, s5, 43
	s_cselect_b64 s[4:5], -1, 0
	v_writelane_b32 v250, s4, 44
	s_cmp_eq_u32 s8, 0
	s_nop 0
	v_writelane_b32 v250, s5, 45
	s_cselect_b64 s[4:5], -1, 0
	v_writelane_b32 v250, s4, 46
	s_nop 1
	v_writelane_b32 v250, s5, 47
	s_lshl_b32 s4, s8, 6
	v_writelane_b32 v250, s4, 48
	s_lshl_b32 s4, s8, 8
	s_add_u32 s2, s2, s4
	s_addc_u32 s3, s3, 0
	s_add_u32 s2, s2, 0x1400
	s_addc_u32 s3, s3, 0
	v_writelane_b32 v250, s2, 49
	s_nop 1
	v_writelane_b32 v250, s3, 50
	s_add_u32 s2, s0, 0x7400
	s_addc_u32 s3, s1, 0
	v_writelane_b32 v250, s2, 51
	s_add_u32 s0, s0, 0x7500
	s_addc_u32 s1, s1, 0
	v_writelane_b32 v250, s3, 52
	v_writelane_b32 v250, s0, 53
	s_nop 1
	v_writelane_b32 v250, s1, 54
	s_load_dwordx4 s[0:3], s[94:95], 0xc8
	s_waitcnt lgkmcnt(0)
	s_add_u32 s4, s2, 0x3a78000
	v_writelane_b32 v250, s4, 55
	s_addc_u32 s4, s3, 0
	v_writelane_b32 v250, s4, 56
	s_add_u32 s4, s0, 0x4200000
	v_writelane_b32 v250, s4, 57
	s_addc_u32 s4, s1, 0
	v_writelane_b32 v250, s4, 58
	s_add_u32 s4, s2, 0x100000
	v_writelane_b32 v250, s4, 59
	v_writelane_b32 v250, s0, 60
	s_nop 1
	v_writelane_b32 v250, s1, 61
	v_writelane_b32 v250, s2, 62
	v_writelane_b32 v250, s3, 63
	s_addc_u32 s0, s3, 0
	v_writelane_b32 v251, s0, 0
	s_add_i32 s0, 0, 0x1af00
	v_writelane_b32 v251, s0, 1
	s_add_i32 s0, 0, 0x16700
	v_writelane_b32 v251, s0, 2
	s_add_i32 s0, 0, 0x14300
	v_writelane_b32 v251, s0, 3
	s_add_i32 s0, 0, 0x13d00
	v_writelane_b32 v251, s0, 4
	s_add_i32 s0, 0, 0xea08
	v_writelane_b32 v251, s0, 5
	v_writelane_b32 v251, s80, 6
	v_writelane_b32 v251, s81, 7
	v_writelane_b32 v251, s82, 8
	s_nop 1
	v_writelane_b32 v251, s83, 9
	v_writelane_b32 v251, s84, 10
	s_nop 1
	v_writelane_b32 v251, s85, 11
	v_writelane_b32 v251, s86, 12
	s_nop 1
	v_writelane_b32 v251, s87, 13
	v_writelane_b32 v251, s60, 14
	s_nop 1
	v_writelane_b32 v251, s61, 15
	v_writelane_b32 v251, s76, 16
	s_nop 1
	v_writelane_b32 v251, s77, 17
	v_writelane_b32 v251, s78, 18
	s_nop 1
	v_writelane_b32 v251, s79, 19
	v_writelane_b32 v251, s64, 20
	s_nop 1
	v_writelane_b32 v251, s65, 21
	v_writelane_b32 v251, s66, 22
	s_nop 1
	v_writelane_b32 v251, s67, 23
	v_writelane_b32 v251, s68, 24
	s_nop 1
	v_writelane_b32 v251, s69, 25
	v_writelane_b32 v251, s62, 26
	s_nop 1
	v_writelane_b32 v251, s63, 27
	v_writelane_b32 v251, s72, 28
	s_nop 1
	v_writelane_b32 v251, s73, 29
	s_mov_b32 s98, 0
	s_nop 0
	v_writelane_b32 v255, s98, 40
	s_branch .LBB0_19

.LBB0_17:
	s_or_b64 exec, exec, s[0:1]
	s_waitcnt lgkmcnt(0)
.LBB0_18:
	s_add_i32 s96, s96, 1
	s_cmp_ge_i32 s96, s97
	s_cbranch_scc0 .LBB0_19
	s_getpc_b64 s[98:99]

.LBB0_19:
	s_cmp_lt_i32 s96, 2
	s_cselect_b64 s[2:3], -1, 0
	s_add_i32 s5, s96, -2
	s_mul_hi_u32 s0, s5, 0x38e38e39
	s_lshr_b32 s4, s0, 1
	s_cmp_eq_u32 s96, 20
	s_cselect_b64 s[10:11], -1, 0
	s_cmp_lg_u32 s96, 20
	s_cselect_b64 s[0:1], -1, 0
	v_writelane_b32 v251, s0, 30
	s_mul_i32 s6, s4, 9
	s_sub_i32 s5, s5, s6
	v_writelane_b32 v251, s1, 31
	s_or_b64 s[0:1], s[2:3], s[10:11]
	s_and_b64 s[0:1], s[0:1], exec
	s_cselect_b32 s5, -1, s5
	s_cmp_eq_u32 s5, 6
	s_cselect_b64 s[0:1], -1, 0
	s_cmp_eq_u32 s96, 1
	s_cselect_b64 s[6:7], -1, 0
	s_or_b64 s[6:7], s[6:7], s[0:1]
	s_and_b64 vcc, exec, s[6:7]
	s_cbranch_vccnz .LBB0_18
	s_and_b64 s[2:3], s[2:3], exec
	s_cselect_b32 s4, 0, s4
	s_cmp_eq_u32 s5, 0
	s_cselect_b64 s[2:3], -1, 0
	s_cmp_eq_u32 s4, 1
	s_cselect_b64 s[6:7], -1, 0
	s_cmp_lg_u32 s4, 1
	v_writelane_b32 v251, s5, 32
	s_mov_b32 s8, s4
	s_cselect_b64 s[4:5], -1, 0
	v_writelane_b32 v251, s4, 33
	s_nop 1
	v_writelane_b32 v251, s5, 34
	v_writelane_b32 v251, s6, 35
	s_and_b64 s[4:5], s[2:3], s[6:7]
	s_nop 0
	v_writelane_b32 v251, s7, 36
	s_and_b64 s[6:7], s[82:83], s[10:11]
	s_or_b64 s[4:5], s[4:5], s[6:7]
	s_and_b64 vcc, exec, s[4:5]
	s_cbranch_vccnz .LBB0_18
	s_cmp_lg_u32 s96, 0
	v_writelane_b32 v251, s10, 37
	s_cselect_b64 s[16:17], -1, 0
	s_cmp_eq_u32 s8, 0
	v_writelane_b32 v251, s11, 38
	s_cselect_b64 s[4:5], -1, 0
	v_writelane_b32 v251, s4, 39
	s_cmp_lg_u32 s8, 0
	s_mov_b32 s6, s8
	v_writelane_b32 v251, s5, 40
	s_cselect_b64 s[4:5], -1, 0
	v_writelane_b32 v251, s4, 41
	s_mov_b32 s7, s55
	s_mov_b32 s41, s93
	v_writelane_b32 v251, s5, 42
	s_mov_b32 s35, s92
	v_readlane_b32 s4, v251, 32
	s_cmp_eq_u32 s4, 8
	s_cselect_b64 s[8:9], -1, 0
	v_writelane_b32 v251, s8, 43
	s_cmp_lg_u32 s4, 8
	s_cselect_b64 s[4:5], -1, 0
	v_writelane_b32 v251, s9, 44
	s_lshl_b64 s[8:9], s[6:7], 23
	v_writelane_b32 v251, s8, 45
	s_lshl_b32 s42, s6, 1
	v_readlane_b32 s12, v250, 60
	v_writelane_b32 v251, s9, 46
	s_mul_i32 s8, s6, 0x21000
	v_writelane_b32 v251, s8, 47
	s_mul_hi_u32 s8, s42, 0x10800
	v_writelane_b32 v251, s8, 48
	s_mul_i32 s8, s6, 0x600000
	v_writelane_b32 v251, s8, 49
	s_mul_hi_u32 s8, s42, 0x300000
	v_writelane_b32 v251, s8, 50
	s_lshl_b32 s8, s6, 10
	s_mov_b32 s9, s55
	v_writelane_b32 v251, s8, 51
	v_readlane_b32 s14, v250, 62
	v_readlane_b32 s15, v250, 63
	v_writelane_b32 v251, s9, 52
	s_mul_hi_u32 s8, s6, 0x318000
	v_writelane_b32 v251, s8, 53
	v_writelane_b32 v251, s6, 54
	s_mov_b32 s8, s55
	s_ashr_i32 s9, s8, 31
	v_writelane_b32 v251, s7, 55
	s_mul_i32 s6, s6, 0x318000
	v_writelane_b32 v251, s6, 56
	s_add_u32 s6, s14, s8
	v_add_u32_e32 v214, s81, v226
	v_and_b32_e32 v0, 64, v226
	s_addc_u32 s7, s15, s9
	v_add_u32_e32 v0, 64, v0
	v_xor_b32_e32 v1, 16, v226
	v_writelane_b32 v251, s6, 57
	v_readfirstlane_b32 s52, v214
	v_cmp_lt_i32_e32 vcc, v1, v0
	v_writelane_b32 v251, s7, 58
	s_ashr_i32 s6, s52, 6
	v_cndmask_b32_e32 v1, v226, v1, vcc
	v_writelane_b32 v251, s6, 59
	v_lshlrev_b32_e32 v233, 2, v1
	v_xor_b32_e32 v1, 32, v226
	v_writelane_b32 v251, s16, 60
	v_cmp_lt_i32_e32 vcc, v1, v0
	s_mov_b64 s[10:11], s[8:9]
	v_writelane_b32 v251, s17, 61
	v_cndmask_b32_e32 v1, v226, v1, vcc
	v_writelane_b32 v251, s41, 62
	v_writelane_b32 v252, s8, 0
	v_lshlrev_b32_e32 v234, 2, v1
	v_readlane_b32 s13, v250, 61
	v_and_b32_e32 v235, 63, v214
	v_readlane_b32 s98, v255, 40
	v_readlane_b32 s99, v251, 7
	s_nop 3
	s_cmp_eq_u32 s98, 0
	s_cbranch_scc1 .Lxw_bar
	s_mov_b32 s98, 0
	s_nop 0
	v_writelane_b32 v255, s98, 40
	s_cmp_lg_u32 s99, 0
	s_cbranch_scc1 .Lxw_bar
	s_mov_b64 exec, 1
	v_readlane_b32 s98, v251, 6
	s_nop 3
	v_mov_b32_e32 v2, s98
	ds_read2_b32 v[2:3], v2 offset0:1 offset1:2
	v_readlane_b32 s98, v250, 51
	v_readlane_b32 s99, v250, 52
	s_waitcnt lgkmcnt(0)
	v_mad_u32_u24 v2, v3, v2, v2
	s_nop 4
.Lxw_poll:
	global_load_dword v3, v209, s[98:99] sc1
	s_waitcnt vmcnt(0)
	v_cmp_ge_u32_e32 vcc, v3, v2
	s_cbranch_vccnz .Lxw_done
	s_sleep 1
	s_branch .Lxw_poll
.Lxw_done:
	buffer_inv sc1
	s_waitcnt vmcnt(0)
	s_mov_b64 exec, -1
.Lxw_bar:
	s_waitcnt lgkmcnt(0)
	s_barrier
	s_and_b64 vcc, exec, s[16:17]
	v_writelane_b32 v251, s35, 63
	v_writelane_b32 v252, s9, 1
	s_cbranch_vccz .LBB0_27
	v_xor_b32_e32 v1, 1, v226
	v_cmp_lt_i32_e32 vcc, v1, v0
	s_and_b64 s[0:1], s[0:1], exec
	s_cselect_b32 s6, 1, -1
	v_cndmask_b32_e32 v1, v226, v1, vcc
	s_and_b64 s[0:1], s[2:3], exec
	v_lshlrev_b32_e32 v215, 2, v1
	v_xor_b32_e32 v1, 2, v226
	v_readlane_b32 s0, v251, 37
	v_cmp_lt_i32_e32 vcc, v1, v0
	v_readlane_b32 s1, v251, 38
	s_cselect_b32 s2, 0, s6
	v_cndmask_b32_e32 v1, v226, v1, vcc
	s_and_b64 s[0:1], s[0:1], exec
	v_lshlrev_b32_e32 v236, 2, v1
	v_xor_b32_e32 v1, 4, v226
	s_cselect_b32 s2, 2, s2
	v_cmp_lt_i32_e32 vcc, v1, v0
	s_lshl_b64 s[0:1], s[8:9], 2
	s_add_u32 s0, s12, s0
	v_cndmask_b32_e32 v1, v226, v1, vcc
	v_lshlrev_b32_e32 v237, 2, v1
	v_xor_b32_e32 v1, 8, v226
	s_addc_u32 s1, s13, s1
	v_cmp_lt_i32_e32 vcc, v1, v0
	v_writelane_b32 v252, s0, 2
	s_cmp_lt_i32 s2, 0
	v_cndmask_b32_e32 v0, v226, v1, vcc
	v_writelane_b32 v252, s1, 3
	v_lshlrev_b32_e32 v238, 2, v0
	v_writelane_b32 v252, s2, 4
	s_mov_b64 s[0:1], -1
	s_cbranch_scc1 .LBB0_23
	s_getpc_b64 s[98:99]

.LBB0_1173:
	v_writelane_b32 v255, s4, 40
	s_mov_b64 s[0:1], exec
	s_getpc_b64 s[98:99]
